# phase 6 visits its two row-tile halves in the opposite order (the half Wout wrote last first; the half phase 7 reads first written last)
# speedup vs baseline: 1.0007x; 1.0007x over previous
;     __device__ bool next(int i, Unit& u) const { const long L = (long)i * G + c; if (L >= 128) return false; u.pm = (int)L & 31; u.pn = u.pm >> 4; u.koff = ((int)L >> 5) * 1024; return true; }
;     __host__ __device__ bool next(int i, Unit& u) const {
;         const long L = (long)i * G + c; if (L >= nwg) return false;
;         int wgid = (int)L; { const int q = nwg / NXCD, r = nwg % NXCD, xcd = wgid % NXCD, off = wgid / NXCD; wgid = (xcd < r ? xcd * (q + 1) : r * (q + 1) + (xcd - r) * q) + off; }
;         const int nig = WGM * nN, gid = wgid / nig, fm = gid * WGM, gsz = (nM - fm) < WGM ? (nM - fm) : WGM;
;         u.pm = fm + ((wgid % nig) % gsz); u.pn = (wgid % nig) / gsz; u.koff = 0; return true;
; template <class Epi, class Sched, bool ALIGN_EPI = false, bool SP2 = false>
; __device__ __forceinline__ void gemm_phase(PG8_LAS unsigned char* lds, const Gemm g, const Sched& S, const Epi& E) {
;     ...
;     if (!S.next(0, cur)) return;
.LBB0_989:
	s_mov_b32 s98, 0
	s_add_u32 s100, s78, 0x12f00
	s_addc_u32 s101, s79, 0
	v_readlane_b32 s0, v254, 0
	v_readlane_b32 s1, v254, 1
	s_cmp_lt_i32 s0, 7
	s_cselect_b64 s[0:1], -1, 0
	s_and_b64 s[0:1], s[0:1], s[72:73]
	s_andn2_b64 vcc, exec, s[0:1]
	s_cbranch_vccnz .LBB0_1014
	s_cmpk_gt_i32 s70, 0x7ff
	v_readfirstlane_b32 s4, v184
	s_cbranch_scc1 .LBB0_1014
	s_mov_b32 s5, s70
	s_cmp_lg_u32 s88, 0x100
	s_cbranch_scc1 .Lp6_noswap
	s_addk_i32 s5, 0x400
.Lp6_noswap:
	s_ashr_i32 s14, s70, 31
	s_lshr_b32 s2, s14, 29
	s_add_i32 s7, s5, s2
	s_and_b32 s2, s7, -8
	s_sub_i32 s6, s5, s2
	s_cmp_gt_i32 s6, -1
	s_cbranch_scc0 .LBB0_993
	s_lshl_b32 s5, s6, 8
	s_ashr_i32 s2, s7, 3
	s_cbranch_execz .LBB0_994
	s_branch .LBB0_995

;     __device__ bool next(int i, Unit& u) const { const long L = (long)i * G + c; if (L >= 128) return false; u.pm = (int)L & 31; u.pn = u.pm >> 4; u.koff = ((int)L >> 5) * 1024; return true; }
;     __host__ __device__ bool next(int i, Unit& u) const {
;         const long L = (long)i * G + c; if (L >= nwg) return false;
;         int wgid = (int)L; { const int q = nwg / NXCD, r = nwg % NXCD, xcd = wgid % NXCD, off = wgid / NXCD; wgid = (xcd < r ? xcd * (q + 1) : r * (q + 1) + (xcd - r) * q) + off; }
;         const int nig = WGM * nN, gid = wgid / nig, fm = gid * WGM, gsz = (nM - fm) < WGM ? (nM - fm) : WGM;
;         u.pm = fm + ((wgid % nig) % gsz); u.pn = (wgid % nig) / gsz; u.koff = 0; return true;
; template <class Epi, class Sched, bool ALIGN_EPI = false, bool SP2 = false>
; __device__ __forceinline__ void gemm_phase(PG8_LAS unsigned char* lds, const Gemm g, const Sched& S, const Epi& E) {
;     ...
;         const bool has_next = S.next(ui + 1, nxt);
.LBB0_1000:
	s_add_i32 s51, s51, 1
	s_cmp_eq_u32 s88, 0x100
	s_cselect_b32 s23, 4, 0
	s_xor_b32 s23, s51, s23
	s_mul_i32 s2, s23, s47
	s_mul_hi_u32 s3, s23, s88
	s_add_i32 s3, s3, s2
	s_mul_i32 s2, s23, s88
	s_add_u32 s26, s2, s70
	s_addc_u32 s27, s3, s14
	v_cmp_gt_i64_e32 vcc, s[26:27], v[160:161]
	v_cmp_lt_i64_e64 s[2:3], s[26:27], v[158:159]
	s_cbranch_vccnz .LBB0_1006
	s_ashr_i32 s22, s26, 31
	s_lshr_b32 s22, s22, 29
	s_add_i32 s24, s26, s22
	s_and_b32 s22, s24, -8
	s_sub_i32 s25, s26, s22
	s_cmp_gt_i32 s25, -1
	s_mov_b64 s[22:23], -1
	s_cbranch_scc0 .LBB0_1003
	s_lshl_b32 s26, s25, 8
	s_mov_b64 s[22:23], 0
